# speedup vs baseline: 1.0166x; 1.0127x over previous
; DEVI void attn_item(const Params& p, const int l, const int bh, const int qblk, const float lam, const float osc, char* smem) {
;   const int tid = threadIdx.x, wid = tid >> 6, lane = tid & 63, l31 = lane & 31, hi = lane >> 5;
;   const int b = bh / 6, h = bh % 6;
;   const int qg = wid >> 1, m = wid & 1;
;   const int nkt = 2 * qblk + 2;
;   const int my_last = 2 * qblk + (qg >> 1);
;   const u16* PBC = (const u16*)(p.ws + OFF_PBC);
;   const u16* VT = (const u16*)(p.ws + OFF_VT) + (size_t)(b * 6 + h) * 256 * 8192;
;   const u16* KT = (const u16*)(p.ws + OFF_KT) + (size_t)(b * 6 + h) * 256 * 8192;
;   const size_t tok0 = (size_t)b * SEQ_;
;   float* wsc = (float*)smem + wid * 64;
;   char* stg = smem + 2048;
;   float* obuf = (float*)(smem + 2048);
;   constexpr float C = 0.125f * 1.4426950408889634f;
;   bf16x8 qf[4];
;   {
;     const u16* qp = PBC + (tok0 + (size_t)qblk * 128 + qg * 32 + l31) * 1280 + 512 + h * 128 + m * 64 + hi * 8;
; #pragma unroll
;     for (int d0 = 0; d0 < 4; ++d0) qf[d0] = *(const bf16x8*)(qp + d0 * 16);
;   }
;   const int kkey = tid >> 4, kch = tid & 15;
;   const u16* kg = KT + kkey * 128 + kch * 8;
;   const int klds = (kch >> 3) * 8192 + swz(kkey, kch & 7);
;   const int ve = tid >> 3, vj = tid & 7;
;   const u16* vg = VT + ve * 64 + vj * 8;
;   const int vx = (ve >> 1) & 7;
;   const int vlds0 = 16384 + ve * 128 + ((((vj >> 1) * 2 + 0) ^ vx) << 4) + (vj & 1) * 8;
;   const int vlds1 = 16384 + ve * 128 + ((((vj >> 1) * 2 + 1) ^ vx) << 4) + (vj & 1) * 8;
;   bf16x8 sk0, sk1, sv0, sv1;
;   char* kbuf = stg; char* vbuf = stg + 32768;
;     ...
;   for (int i = 0; i < 64; ++i) { d1 += p.in[25][l * 64 + i] * p.in[26][l * 64 + i]; d2 += p.in[27][l * 64 + i] * p.in[28][l * 64 + i]; }
;   const float lam_init = 0.8f - 0.6f * expf(-0.3f * (float)l);
;   const float lam = expf(d1) - expf(d2) + lam_init;
;   const float osc = 1.f - lam_init;
.LBB0_527:
	s_add_u32 s2, s14, s0
	s_addc_u32 s3, s15, s1
	global_load_dwordx4 v[4:7], v1, s[2:3]
	global_load_dwordx4 v[8:11], v1, s[2:3] offset:16
	s_add_u32 s2, s16, s0
	s_addc_u32 s3, s17, s1
	global_load_dwordx4 v[12:15], v1, s[2:3]
	global_load_dwordx4 v[16:19], v1, s[2:3] offset:16
	s_add_u32 s2, s18, s0
	s_addc_u32 s3, s19, s1
	global_load_dwordx4 v[20:23], v1, s[2:3]
	global_load_dwordx4 v[24:27], v1, s[2:3] offset:16
	s_add_u32 s2, s20, s0
	s_addc_u32 s3, s21, s1
	global_load_dwordx4 v[28:31], v1, s[2:3]
	global_load_dwordx4 v[32:35], v1, s[2:3] offset:16
	s_add_u32 s0, s0, 32
	s_addc_u32 s1, s1, 0
	s_cmpk_eq_i32 s0, 0x100
	s_waitcnt vmcnt(7)
	v_mov_b32_e32 v36, v4
	v_mov_b32_e32 v4, v6
	s_waitcnt vmcnt(6)
	v_mov_b32_e32 v6, v8
	v_mov_b32_e32 v8, v10
	s_waitcnt vmcnt(5)
	v_mov_b32_e32 v10, v12
	v_mov_b32_e32 v12, v14
	s_waitcnt vmcnt(3)
	v_mov_b32_e32 v37, v20
	v_mov_b32_e32 v20, v5
	v_mov_b32_e32 v5, v22
	v_mov_b32_e32 v22, v7
	s_waitcnt vmcnt(2)
	v_mov_b32_e32 v7, v24
	v_mov_b32_e32 v24, v9
	v_mov_b32_e32 v9, v26
	v_mov_b32_e32 v26, v11
	s_waitcnt vmcnt(1)
	v_mov_b32_e32 v11, v28
	v_mov_b32_e32 v28, v13
	v_pk_fma_f32 v[2:3], v[36:37], v[10:11], v[2:3]
	v_mov_b32_e32 v13, v30
	v_pk_fma_f32 v[2:3], v[20:21], v[28:29], v[2:3]
	v_mov_b32_e32 v30, v15
	v_pk_fma_f32 v[2:3], v[4:5], v[12:13], v[2:3]
	v_mov_b32_e32 v14, v16
	s_waitcnt vmcnt(0)
	v_mov_b32_e32 v15, v32
	v_pk_fma_f32 v[2:3], v[22:23], v[30:31], v[2:3]
	v_mov_b32_e32 v32, v17
	v_pk_fma_f32 v[2:3], v[6:7], v[14:15], v[2:3]
	v_mov_b32_e32 v16, v18
	v_mov_b32_e32 v17, v34
	v_pk_fma_f32 v[2:3], v[24:25], v[32:33], v[2:3]
	v_mov_b32_e32 v34, v19
	v_pk_fma_f32 v[2:3], v[8:9], v[16:17], v[2:3]
	s_nop 0
	v_pk_fma_f32 v[2:3], v[26:27], v[34:35], v[2:3]
	s_cbranch_scc0 .LBB0_527
	v_mul_f32_e32 v1, 0x3fb8aa3b, v2
	s_mov_b32 s0, 0x3fb8aa3b
	v_rndne_f32_e32 v4, v1
	v_sub_f32_e32 v5, v1, v4
	v_fma_f32 v1, v2, s0, -v1
	v_fmac_f32_e32 v1, 0x32a5705f, v2
	v_add_f32_e32 v1, v5, v1
	v_exp_f32_e32 v1, v1
	v_cvt_i32_f32_e32 v4, v4
	s_mov_b32 s1, 0xc2ce8ed0
	v_cmp_ngt_f32_e32 vcc, s1, v2
	s_mov_b32 s2, 0x42b17218
	v_ldexp_f32 v1, v1, v4
	v_mul_f32_e32 v4, 0x3fb8aa3b, v3
	v_rndne_f32_e32 v5, v4
	v_sub_f32_e32 v6, v4, v5
	v_fma_f32 v4, v3, s0, -v4
	v_fmac_f32_e32 v4, 0x32a5705f, v3
	v_add_f32_e32 v4, v6, v4
	v_exp_f32_e32 v4, v4
	v_cvt_i32_f32_e32 v5, v5
	v_cndmask_b32_e32 v1, 0, v1, vcc
	v_mov_b32_e32 v6, 0x7f800000
	v_cmp_nlt_f32_e32 vcc, s2, v2
	v_ldexp_f32 v2, v4, v5
	v_bfe_u32 v9, v0, 4, 6
	v_cndmask_b32_e32 v1, v6, v1, vcc
	v_cmp_ngt_f32_e32 vcc, s1, v3
	v_lshlrev_b32_e32 v10, 7, v9
	v_and_b32_e32 v14, 6, v0
	v_cndmask_b32_e32 v2, 0, v2, vcc
	v_cmp_nlt_f32_e32 vcc, s2, v3
	s_movk_i32 s2, 0x3ff
	v_bfe_u32 v3, v0, 5, 5
	v_cndmask_b32_e32 v2, v6, v2, vcc
	v_sub_f32_e32 v1, v1, v2
	v_bitop3_b32 v6, v3, v0, s2 bitop3:0x78
	v_add_f32_e32 v196, 0x3e4ccccc, v1
	v_and_b32_e32 v1, 0x3ff, v0
	v_lshlrev_b32_e32 v6, 4, v6
	v_lshl_or_b32 v12, v1, 10, v6
	s_movk_i32 s2, 0x2070
	v_and_or_b32 v17, v12, s2, v10
	v_bfe_u32 v10, v0, 1, 3
	v_bfe_u32 v195, v1, 5, 1
	v_bitop3_b32 v3, v3, v10, 1 bitop3:0x6c
	v_lshlrev_b32_e32 v202, 4, v3
	v_bitop3_b32 v3, v195, v10, 2 bitop3:0x36
	v_lshlrev_b32_e32 v203, 4, v3
	v_bitop3_b32 v3, v195, v10, 4 bitop3:0x36
	v_and_b32_e32 v166, 31, v0
	v_bfe_u32 v168, v0, 2, 8
	v_lshlrev_b32_e32 v11, 3, v1
	v_lshlrev_b32_e32 v16, 4, v1
	v_bitop3_b32 v15, v9, v14, 7 bitop3:0x6c
	v_lshlrev_b32_e32 v204, 4, v3
	v_bitop3_b32 v3, v195, v10, 6 bitop3:0x36
	v_and_b32_e32 v8, 0x60, v168
	v_mov_b32_e32 v173, 0
	v_bfe_u32 v13, v1, 4, 3
	v_and_b32_e32 v6, 0x1f80, v16
	v_lshlrev_b32_e32 v15, 4, v15
	v_and_b32_e32 v198, 8, v11
	v_lshlrev_b32_e32 v205, 4, v3
	v_lshlrev_b32_e32 v199, 2, v166
	v_and_b32_e32 v3, 64, v1
	v_lshlrev_b32_e32 v172, 8, v9
	v_bfe_u32 v5, v1, 6, 1
	v_and_b32_e32 v7, 0x1c0, v0
	v_bitop3_b32 v11, v14, v13, 1 bitop3:0x36
	v_or3_b32 v18, v15, v6, v198
	v_lshl_add_u32 v200, v166, 7, 16
	v_cmp_ne_u32_e64 s[6:7], 0, v3
	v_lshl_or_b32 v3, v195, 2, v8
	v_add_u32_e32 v171, 16, v199
	s_movk_i32 s8, 0x240
	v_lshl_add_u64 v[12:13], s[28:29], 0, v[172:173]
	v_and_b32_e32 v14, 0xf0, v16
	v_mov_b32_e32 v15, v173
	v_lshlrev_b32_e32 v2, 6, v5
	v_lshl_add_u32 v201, v5, 13, v200
	v_lshl_add_u32 v206, v7, 2, 16
	v_cmp_eq_u32_e64 s[4:5], 0, v5
	v_mad_u32_u24 v208, v3, s8, v171
	v_and_b32_e32 v3, 3, v0
	v_mad_u32_u24 v5, v168, s8, 16
	v_lshl_add_u64 v[12:13], v[12:13], 0, v[14:15]
	s_mov_b64 s[8:9], 0x22a00000
	v_mov_b32_e32 v7, v173
	v_or_b32_e32 v170, v8, v166
	v_lshlrev_b32_e32 v11, 4, v11
	v_lshlrev_b32_e32 v8, 4, v3
	v_lshlrev_b32_e32 v10, 2, v3
	v_lshl_add_u64 v[174:175], v[12:13], 0, s[8:9]
	v_lshl_add_u64 v[12:13], s[28:29], 0, v[6:7]
	v_and_b32_e32 v14, 0x70, v16
	v_and_b32_e32 v3, 15, v0
	s_add_u32 s10, s28, 0x3dd80000
	v_lshlrev_b32_e32 v4, 3, v195
	v_or3_b32 v11, v11, v6, v198
	v_lshl_add_u64 v[12:13], v[12:13], 0, v[14:15]
	s_mov_b64 s[8:9], 0x25a00000
	v_mov_b32_e32 v9, v173
	v_lshl_or_b32 v180, v3, 4, v172
	v_and_b32_e32 v3, 7, v0
	v_lshlrev_b32_e32 v184, 1, v2
	v_mbcnt_lo_u32_b32 v2, -1, 0
	s_mov_b32 s73, 0
	s_addc_u32 s34, s29, 0
	v_cmp_eq_u32_e64 s[0:1], 0, v1
	v_bfe_u32 v167, v0, 6, 4
	v_bfe_u32 v197, v0, 8, 2
	v_cmp_eq_u32_e64 s[2:3], 0, v195
	v_add_u32_e32 v207, v206, v199
	v_lshlrev_b32_e32 v194, 4, v195
	v_mov_b32_e32 v169, v173
	v_lshl_add_u64 v[176:177], v[12:13], 0, s[8:9]
	v_lshl_add_u64 v[178:179], s[22:23], 0, v[8:9]
	v_mov_b32_e32 v181, v173
	v_lshl_or_b32 v182, v3, 4, v6
	v_mov_b32_e32 v183, v173
	v_lshlrev_b32_e32 v186, 1, v4
	s_movk_i32 s35, 0x2000
	s_mov_b32 s36, 0x42800000
	s_mov_b32 s78, 0x3e38aa3b
	v_add_u32_e32 v209, v5, v8
	v_mov_b32_e32 v210, 0x3727c5ac
	v_lshlrev_b32_e32 v172, 1, v10
	v_mov_b32_e32 v211, 0xa00
	v_add_u32_e32 v212, 16, v17
	v_add_u32_e32 v213, 16, v18
	v_add_u32_e32 v214, 16, v11
	v_mbcnt_hi_u32_b32 v193, -1, v2
	s_mov_b32 s37, 0
	v_lshrrev_b32_e32 v180, 3, v0
	v_bfe_u32 v181, v0, 4, 3
	v_and_b32_e32 v188, 7, v0
	v_xor_b32_e32 v181, v188, v181
	v_lshlrev_b32_e32 v180, 8, v180
	v_lshl_or_b32 v180, v181, 4, v180
	v_mov_b32_e32 v181, 0
	v_readfirstlane_b32 s101, v0
	s_lshr_b32 s101, s101, 6
	s_lshl_b32 s101, s101, 10
	s_branch .LBB0_530

; #define K_LOAD(kt) do { sk0 = *(const bf16x8*)(kg + (size_t)(kt) * 8192); sk1 = *(const bf16x8*)(kg + (size_t)(kt) * 8192 + 4096); } while (0)
; #define V_LOAD(kt) do { sv0 = *(const bf16x8*)(vg + (size_t)(kt) * 8192); sv1 = *(const bf16x8*)(vg + (size_t)(kt) * 8192 + 4096); } while (0)
; #define K_STORE(bi) do { char* s_ = kbuf + (bi) * 16384; *(bf16x8*)(s_ + klds) = sk0; *(bf16x8*)(s_ + klds + 4096) = sk1; } while (0)
; #define V_STORE(bi) do { char* s_ = vbuf + (bi) * 16384 - 16384; \
;     s16x4 a0_ = {sv0[0], sv0[1], sv0[2], sv0[3]}, a1_ = {sv0[4], sv0[5], sv0[6], sv0[7]}; \
;     s16x4 b0_ = {sv1[0], sv1[1], sv1[2], sv1[3]}, b1_ = {sv1[4], sv1[5], sv1[6], sv1[7]}; \
;     *(s16x4*)(s_ + vlds0) = a0_; *(s16x4*)(s_ + vlds1) = a1_; *(s16x4*)(s_ + vlds0 + 8192) = b0_; *(s16x4*)(s_ + vlds1 + 8192) = b1_; } while (0)
; DEVI void attn_item(const Params& p, const int l, const int bh, const int qblk, const float lam, const float osc, char* smem) {
;     ...
;   f32x16 o[4];
; #pragma unroll
;   for (int d0 = 0; d0 < 4; ++d0)
; #pragma unroll
;     for (int r = 0; r < 16; ++r) o[d0][r] = 0.f;
;   float m_reg = -1e30f, l_reg = 0.f;
;   const int xq = (l31 >> 1) & 7;
;   f32x16 pA0, pA1, pB0, pB1;
;   K_LOAD(0); V_LOAD(0);
;   {
;     const bf16x8 tk0 = *(const bf16x8*)(kg + (size_t)8192), tk1 = *(const bf16x8*)(kg + (size_t)8192 + 4096);
;     K_STORE(0); V_STORE(0);
;     sk0 = tk0; sk1 = tk1; K_STORE(1);
;   }
;   __syncthreads();
;   QK_TILE(pA0, pA1, 0);
;   __syncthreads();
.LBB0_540:
	s_cmp_lt_u32 s52, s88
	s_cselect_b64 s[58:59], -1, 0
	s_cmp_ge_u32 s52, s88
	s_cselect_b64 s[56:57], -1, 0
	s_and_b64 vcc, exec, s[56:57]
	v_lshl_add_u64 v[188:189], s[54:55], 0, v[180:181]
	s_cbranch_vccnz .LBB0_542
	v_add_co_u32_e32 v146, vcc, 0x22a08000, v188
	s_nop 1
	v_addc_co_u32_e32 v147, vcc, 0, v189, vcc
	s_add_u32 m0, s101, 0x810
	s_nop 0
	global_load_lds_dwordx4 v[146:147], off
	s_add_u32 m0, s101, 0x2790
	s_nop 0
	global_load_lds_dwordx4 v[146:147], off offset:128
.LBB0_542:
	v_lshl_add_u64 v[190:191], s[54:55], 0, v[182:183]
	v_add_co_u32_e32 v154, vcc, 0x25a04000, v190
	s_nop 1
	v_addc_co_u32_e32 v155, vcc, 0, v191, vcc
	v_add_co_u32_e32 v158, vcc, 0x25a06000, v190
	s_nop 1
	v_addc_co_u32_e32 v159, vcc, 0, v191, vcc
	global_load_dwordx4 v[154:157], v[154:155], off
	s_nop 0
	global_load_dwordx4 v[158:161], v[158:159], off
	v_cmp_le_u32_e32 vcc, s52, v217
	s_and_saveexec_b64 s[8:9], vcc
	s_cbranch_execz .LBB0_548
	ds_read_b128 v[98:101], v185 offset:18432
	ds_read_b128 v[114:117], v185 offset:22528
	s_waitcnt lgkmcnt(1)
	v_mfma_f32_32x32x16_bf16 v[98:113], v[98:101], v[130:133], 0
	ds_read_b128 v[118:121], v187 offset:18432
	ds_read_b128 v[220:223], v187 offset:22528
	s_waitcnt lgkmcnt(1)
	v_mfma_f32_32x32x16_bf16 v[98:113], v[118:121], v[134:137], v[98:113]
	ds_read_b128 v[118:121], v215 offset:18432
	s_waitcnt lgkmcnt(0)
	v_mfma_f32_32x32x16_bf16 v[98:113], v[118:121], v[138:141], v[98:113]
	ds_read_b128 v[118:121], v216 offset:18432
	s_waitcnt lgkmcnt(0)
	v_mfma_f32_32x32x16_bf16 v[98:113], v[118:121], v[142:145], v[98:113]
	v_max_f32_e32 v118, v67, v67
	v_max_f32_e32 v119, v66, v66
	v_max_f32_e32 v118, v119, v118
	v_max3_f32 v118, v118, v68, v69
	v_max3_f32 v118, v118, v70, v71
	v_max3_f32 v118, v118, v72, v73
	v_max3_f32 v118, v118, v74, v75
	v_max3_f32 v118, v118, v76, v77
	v_max3_f32 v118, v118, v78, v79
	v_max3_f32 v219, v118, v80, v81
	v_mfma_f32_32x32x16_bf16 v[114:129], v[114:117], v[130:133], 0
	v_max3_f32 v219, v219, v82, v83
	v_max3_f32 v219, v219, v84, v85
	v_max3_f32 v219, v219, v86, v87
	v_max3_f32 v219, v219, v88, v89
	v_max3_f32 v219, v219, v90, v91
	v_max3_f32 v219, v219, v92, v93
	v_max3_f32 v219, v219, v94, v95
	v_max3_f32 v219, v219, v96, v97
	v_mfma_f32_32x32x16_bf16 v[114:129], v[220:223], v[134:137], v[114:129]
	v_mov_b32_e32 v220, v219
	s_nop 1
	v_permlane32_swap_b32_e32 v219, v220
	v_max_f32_e32 v220, v220, v220
	v_max_f32_e32 v219, v219, v219
	v_max_f32_e32 v219, v219, v220
	v_sub_f32_e32 v220, v219, v192
	v_cmp_ge_f32_e32 vcc, s36, v220
	s_cmp_eq_u64 vcc, exec
	v_max_f32_e32 v220, v192, v192
	s_cselect_b64 vcc, -1, 0
	v_max_f32_e32 v219, v220, v219
	v_cndmask_b32_e32 v219, v219, v192, vcc
	v_sub_f32_e32 v192, v192, v219
	v_mul_f32_e32 v192, 0x3e38aa3b, v192
	v_exp_f32_e32 v220, v192
	v_mul_f32_e32 v192, 0xbe38aa3b, v219
	v_pk_fma_f32 v[96:97], v[96:97], s[78:79], v[192:193] op_sel_hi:[1,0,0]
	ds_read_b128 v[224:227], v215 offset:22528
	v_pk_fma_f32 v[86:87], v[86:87], s[78:79], v[192:193] op_sel_hi:[1,0,0]
	v_pk_fma_f32 v[88:89], v[88:89], s[78:79], v[192:193] op_sel_hi:[1,0,0]
	v_pk_fma_f32 v[90:91], v[90:91], s[78:79], v[192:193] op_sel_hi:[1,0,0]
	v_pk_fma_f32 v[92:93], v[92:93], s[78:79], v[192:193] op_sel_hi:[1,0,0]
	v_pk_fma_f32 v[94:95], v[94:95], s[78:79], v[192:193] op_sel_hi:[1,0,0]
	ds_read_b128 v[162:165], v216 offset:22528
	v_pk_fma_f32 v[84:85], v[84:85], s[78:79], v[192:193] op_sel_hi:[1,0,0]
	s_waitcnt lgkmcnt(1)
	v_mfma_f32_32x32x16_bf16 v[114:129], v[224:227], v[138:141], v[114:129]
	v_fma_f32 v66, v66, s78, v192
	v_fma_f32 v67, v67, s78, v192
	v_fma_f32 v68, v68, s78, v192
	v_fma_f32 v69, v69, s78, v192
	v_exp_f32_e32 v66, v66
	v_exp_f32_e32 v67, v67
	v_exp_f32_e32 v68, v68
	v_exp_f32_e32 v69, v69
	v_pk_fma_f32 v[70:71], v[70:71], s[78:79], v[192:193] op_sel_hi:[1,0,0]
	v_pk_add_f32 v[222:223], v[66:67], 0 op_sel_hi:[1,0]
	v_exp_f32_e32 v70, v70
	v_exp_f32_e32 v71, v71
	v_pk_add_f32 v[222:223], v[68:69], v[222:223]
	v_pk_fma_f32 v[72:73], v[72:73], s[78:79], v[192:193] op_sel_hi:[1,0,0]
	v_exp_f32_e32 v84, v84
	v_pk_add_f32 v[222:223], v[70:71], v[222:223]
	v_exp_f32_e32 v72, v72
	v_exp_f32_e32 v73, v73
	s_waitcnt lgkmcnt(0)
	v_mfma_f32_32x32x16_bf16 v[114:129], v[162:165], v[142:145], v[114:129]
	v_fma_f32 v74, v74, s78, v192
	v_fma_f32 v75, v75, s78, v192
	v_fma_f32 v76, v76, s78, v192
	v_fma_f32 v77, v77, s78, v192
	v_exp_f32_e32 v74, v74
	v_exp_f32_e32 v75, v75
	v_exp_f32_e32 v76, v76
	v_exp_f32_e32 v77, v77
	v_pk_fma_f32 v[78:79], v[78:79], s[78:79], v[192:193] op_sel_hi:[1,0,0]
	v_pk_fma_f32 v[80:81], v[80:81], s[78:79], v[192:193] op_sel_hi:[1,0,0]
	v_exp_f32_e32 v78, v78
	v_exp_f32_e32 v79, v79
	v_pk_add_f32 v[222:223], v[72:73], v[222:223]
	v_exp_f32_e32 v80, v80
	v_exp_f32_e32 v81, v81
	v_pk_fma_f32 v[82:83], v[82:83], s[78:79], v[192:193] op_sel_hi:[1,0,0]
	v_pk_add_f32 v[222:223], v[74:75], v[222:223]
	v_exp_f32_e32 v82, v82
	v_exp_f32_e32 v83, v83
	v_pk_add_f32 v[222:223], v[76:77], v[222:223]
	v_exp_f32_e32 v85, v85
	v_pk_add_f32 v[222:223], v[78:79], v[222:223]
	v_exp_f32_e32 v86, v86
	v_exp_f32_e32 v87, v87
	v_pk_add_f32 v[222:223], v[80:81], v[222:223]
	v_exp_f32_e32 v88, v88
	v_exp_f32_e32 v89, v89
	v_pk_add_f32 v[162:163], v[82:83], v[222:223]
	v_exp_f32_e32 v90, v90
	v_exp_f32_e32 v91, v91
	v_pk_add_f32 v[162:163], v[84:85], v[162:163]
	v_exp_f32_e32 v92, v92
	v_exp_f32_e32 v93, v93
	v_pk_add_f32 v[162:163], v[86:87], v[162:163]
	v_exp_f32_e32 v94, v94
	v_exp_f32_e32 v95, v95
	v_pk_add_f32 v[162:163], v[88:89], v[162:163]
	v_exp_f32_e32 v96, v96
	v_exp_f32_e32 v97, v97
	v_pk_add_f32 v[162:163], v[90:91], v[162:163]
	s_nop 0
	v_pk_add_f32 v[162:163], v[92:93], v[162:163]
	s_nop 0
	v_pk_add_f32 v[162:163], v[94:95], v[162:163]
	s_nop 0
	v_pk_add_f32 v[162:163], v[96:97], v[162:163]
	s_nop 0
	v_pk_add_f32 v[162:163], v[162:163], v[162:163] op_sel:[0,1] op_sel_hi:[1,0]
	s_nop 0
	v_mov_b32_e32 v163, v162
	s_nop 1
	v_permlane32_swap_b32_e32 v162, v163
	s_cbranch_vccnz .LBB0_547
	s_waitcnt lgkmcnt(0)
	s_and_saveexec_b64 s[60:61], s[2:3]
	ds_write_b32 v207, v220
	s_or_b64 exec, exec, s[60:61]
	s_waitcnt lgkmcnt(0)
	v_add_u32_e32 v164, v206, v194
	ds_read_b128 v[222:225], v164 offset:96
	ds_read_b128 v[226:229], v164 offset:64
	ds_read_b128 v[230:233], v164 offset:32
	ds_read_b128 v[234:237], v164
	s_waitcnt lgkmcnt(0)
	s_waitcnt lgkmcnt(3)
	v_pk_mul_f32 v[62:63], v[62:63], v[222:223]
	s_waitcnt lgkmcnt(2)
	v_pk_mul_f32 v[58:59], v[58:59], v[226:227]
	s_waitcnt lgkmcnt(1)
	v_pk_mul_f32 v[54:55], v[54:55], v[230:231]
	v_pk_mul_f32 v[64:65], v[64:65], v[224:225]
	v_pk_mul_f32 v[60:61], v[60:61], v[228:229]
	v_pk_mul_f32 v[56:57], v[56:57], v[232:233]
	s_waitcnt lgkmcnt(0)
	v_pk_mul_f32 v[52:53], v[52:53], v[236:237]
	v_pk_mul_f32 v[50:51], v[50:51], v[234:235]
	v_pk_mul_f32 v[46:47], v[46:47], v[222:223]
	v_pk_mul_f32 v[42:43], v[42:43], v[226:227]
	v_pk_mul_f32 v[38:39], v[38:39], v[230:231]
	v_pk_mul_f32 v[48:49], v[48:49], v[224:225]
	v_pk_mul_f32 v[44:45], v[44:45], v[228:229]
	v_pk_mul_f32 v[40:41], v[40:41], v[232:233]
	v_pk_mul_f32 v[36:37], v[36:37], v[236:237]
	v_pk_mul_f32 v[34:35], v[34:35], v[234:235]
	v_pk_mul_f32 v[30:31], v[30:31], v[222:223]
	v_pk_mul_f32 v[26:27], v[26:27], v[226:227]
	v_pk_mul_f32 v[22:23], v[22:23], v[230:231]
	v_pk_mul_f32 v[32:33], v[32:33], v[224:225]
	v_pk_mul_f32 v[28:29], v[28:29], v[228:229]
	v_pk_mul_f32 v[24:25], v[24:25], v[232:233]
	v_pk_mul_f32 v[20:21], v[20:21], v[236:237]
	v_pk_mul_f32 v[18:19], v[18:19], v[234:235]
	v_pk_mul_f32 v[14:15], v[14:15], v[222:223]
	v_pk_mul_f32 v[10:11], v[10:11], v[226:227]
	v_pk_mul_f32 v[6:7], v[6:7], v[230:231]
	v_pk_mul_f32 v[16:17], v[16:17], v[224:225]
	v_pk_mul_f32 v[12:13], v[12:13], v[228:229]
	v_pk_mul_f32 v[8:9], v[8:9], v[232:233]
	v_pk_mul_f32 v[4:5], v[4:5], v[236:237]
	v_pk_mul_f32 v[2:3], v[2:3], v[234:235]

.LBB0_548:
	s_or_b64 exec, exec, s[8:9]
	v_cndmask_b32_e64 v162, 0, 1, s[58:59]
	v_cmp_ne_u32_e64 s[8:9], 1, v162
	s_andn2_b64 vcc, exec, s[58:59]
	s_cbranch_vccnz .LBB0_550
	s_waitcnt vmcnt(2)

.LBB0_555:
	v_add_co_u32_e32 v146, vcc, 0x22a0c000, v188
	s_nop 1
	v_addc_co_u32_e32 v147, vcc, 0, v189, vcc
	s_add_u32 m0, s101, 0x4810
	s_nop 0
	global_load_lds_dwordx4 v[146:147], off
	s_add_u32 m0, s101, 0x6790
	s_nop 0
	global_load_lds_dwordx4 v[146:147], off offset:128
	s_and_b64 vcc, exec, s[8:9]
	s_cbranch_vccnz .LBB0_552

.LBB0_562:
	s_waitcnt vmcnt(0)
	s_and_b64 vcc, exec, s[8:9]
	s_cbranch_vccnz .LBB0_539

; DEVI void attn_item(const Params& p, const int l, const int bh, const int qblk, const float lam, const float osc, char* smem) {
;   const int tid = threadIdx.x, wid = tid >> 6, lane = tid & 63, l31 = lane & 31, hi = lane >> 5;
;   const int b = bh / 6, h = bh % 6;
;   const int qg = wid >> 1, m = wid & 1;
;   const int nkt = 2 * qblk + 2;
;   const int my_last = 2 * qblk + (qg >> 1);
;   const u16* PBC = (const u16*)(p.ws + OFF_PBC);
;   const u16* VT = (const u16*)(p.ws + OFF_VT) + (size_t)(b * 6 + h) * 256 * 8192;
;   const u16* KT = (const u16*)(p.ws + OFF_KT) + (size_t)(b * 6 + h) * 256 * 8192;
;   const size_t tok0 = (size_t)b * SEQ_;
;   float* wsc = (float*)smem + wid * 64;
;   char* stg = smem + 2048;
;   float* obuf = (float*)(smem + 2048);
;   constexpr float C = 0.125f * 1.4426950408889634f;
;   bf16x8 qf[4];
;   {
;     const u16* qp = PBC + (tok0 + (size_t)qblk * 128 + qg * 32 + l31) * 1280 + 512 + h * 128 + m * 64 + hi * 8;
; #pragma unroll
;     for (int d0 = 0; d0 < 4; ++d0) qf[d0] = *(const bf16x8*)(qp + d0 * 16);
;   }
;   const int kkey = tid >> 4, kch = tid & 15;
;   const u16* kg = KT + kkey * 128 + kch * 8;
;   const int klds = (kch >> 3) * 8192 + swz(kkey, kch & 7);
;   const int ve = tid >> 3, vj = tid & 7;
;   const u16* vg = VT + ve * 64 + vj * 8;
;   const int vx = (ve >> 1) & 7;
;   const int vlds0 = 16384 + ve * 128 + ((((vj >> 1) * 2 + 0) ^ vx) << 4) + (vj & 1) * 8;
;   const int vlds1 = 16384 + ve * 128 + ((((vj >> 1) * 2 + 1) ^ vx) << 4) + (vj & 1) * 8;
;   bf16x8 sk0, sk1, sv0, sv1;
;   char* kbuf = stg; char* vbuf = stg + 32768;
;     ...
;   for (int i = 0; i < 64; ++i) { d1 += p.in[25][l * 64 + i] * p.in[26][l * 64 + i]; d2 += p.in[27][l * 64 + i] * p.in[28][l * 64 + i]; }
;   const float lam_init = 0.8f - 0.6f * expf(-0.3f * (float)l);
;   const float lam = expf(d1) - expf(d2) + lam_init;
;   const float osc = 1.f - lam_init;
.LBB0_1303:
	s_add_u32 s2, s14, s0
	s_addc_u32 s3, s15, s1
	global_load_dwordx4 v[6:9], v4, s[2:3] offset:256
	global_load_dwordx4 v[10:13], v4, s[2:3] offset:272
	s_add_u32 s2, s16, s0
	s_addc_u32 s3, s17, s1
	global_load_dwordx4 v[14:17], v4, s[2:3] offset:256
	global_load_dwordx4 v[18:21], v4, s[2:3] offset:272
	s_add_u32 s2, s18, s0
	s_addc_u32 s3, s19, s1
	global_load_dwordx4 v[22:25], v4, s[2:3] offset:256
	global_load_dwordx4 v[26:29], v4, s[2:3] offset:272
	s_add_u32 s2, s20, s0
	s_addc_u32 s3, s21, s1
	global_load_dwordx4 v[30:33], v4, s[2:3] offset:256
	global_load_dwordx4 v[34:37], v4, s[2:3] offset:272
	s_add_u32 s0, s0, 32
	s_addc_u32 s1, s1, 0
	s_cmpk_eq_i32 s0, 0x100
	s_waitcnt vmcnt(0)
	v_mov_b32_e32 v38, v6
	v_mov_b32_e32 v6, v8
	v_mov_b32_e32 v8, v10
	v_mov_b32_e32 v10, v12
	v_mov_b32_e32 v12, v14
	v_mov_b32_e32 v14, v16
	v_mov_b32_e32 v39, v22
	v_mov_b32_e32 v22, v7
	v_mov_b32_e32 v7, v24
	v_mov_b32_e32 v24, v9
	v_mov_b32_e32 v9, v26
	v_mov_b32_e32 v26, v11
	v_mov_b32_e32 v11, v28
	v_mov_b32_e32 v28, v13
	v_mov_b32_e32 v13, v30
	v_mov_b32_e32 v30, v15
	v_pk_fma_f32 v[2:3], v[38:39], v[12:13], v[2:3]
	v_mov_b32_e32 v15, v32
	v_pk_fma_f32 v[2:3], v[22:23], v[30:31], v[2:3]
	v_mov_b32_e32 v32, v17
	v_pk_fma_f32 v[2:3], v[6:7], v[14:15], v[2:3]
	v_mov_b32_e32 v16, v18
	v_mov_b32_e32 v17, v34
	v_pk_fma_f32 v[2:3], v[24:25], v[32:33], v[2:3]
	v_mov_b32_e32 v34, v19
	v_pk_fma_f32 v[2:3], v[8:9], v[16:17], v[2:3]
	v_mov_b32_e32 v18, v20
	v_mov_b32_e32 v19, v36
	v_pk_fma_f32 v[2:3], v[26:27], v[34:35], v[2:3]
	v_mov_b32_e32 v36, v21
	v_pk_fma_f32 v[2:3], v[10:11], v[18:19], v[2:3]
	s_nop 0
	v_pk_fma_f32 v[2:3], v[28:29], v[36:37], v[2:3]
	s_cbranch_scc0 .LBB0_1303
	v_mul_f32_e32 v4, 0x3fb8aa3b, v2
	s_mov_b32 s0, 0x3fb8aa3b
	v_rndne_f32_e32 v5, v4
	v_sub_f32_e32 v6, v4, v5
	v_fma_f32 v4, v2, s0, -v4
	v_fmac_f32_e32 v4, 0x32a5705f, v2
	v_add_f32_e32 v4, v6, v4
	v_exp_f32_e32 v4, v4
	v_cvt_i32_f32_e32 v5, v5
	s_mov_b32 s1, 0xc2ce8ed0
	v_cmp_ngt_f32_e32 vcc, s1, v2
	s_mov_b32 s2, 0x42b17218
	v_ldexp_f32 v4, v4, v5
	v_mul_f32_e32 v5, 0x3fb8aa3b, v3
	v_rndne_f32_e32 v6, v5
	v_sub_f32_e32 v7, v5, v6
	v_fma_f32 v5, v3, s0, -v5
	v_fmac_f32_e32 v5, 0x32a5705f, v3
	v_add_f32_e32 v5, v7, v5
	v_exp_f32_e32 v5, v5
	v_cvt_i32_f32_e32 v6, v6
	v_cndmask_b32_e32 v4, 0, v4, vcc
	v_mov_b32_e32 v7, 0x7f800000
	v_cmp_nlt_f32_e32 vcc, s2, v2
	v_and_b32_e32 v163, 0x3ff, v0
	v_lshlrev_b32_e32 v9, 7, v42
	v_cndmask_b32_e32 v2, v7, v4, vcc
	v_ldexp_f32 v4, v5, v6
	v_cmp_ngt_f32_e32 vcc, s1, v3
	v_bfe_u32 v192, v163, 5, 1
	v_and_b32_e32 v13, 6, v0
	v_cndmask_b32_e32 v4, 0, v4, vcc
	v_cmp_nlt_f32_e32 vcc, s2, v3
	s_movk_i32 s2, 0x3ff
	v_and_b32_e32 v162, 31, v0
	v_cndmask_b32_e32 v3, v7, v4, vcc
	v_sub_f32_e32 v2, v2, v3
	v_bfe_u32 v3, v0, 5, 5
	v_bitop3_b32 v6, v3, v0, s2 bitop3:0x78
	v_lshlrev_b32_e32 v6, 4, v6
	v_lshl_or_b32 v11, v163, 10, v6
	s_movk_i32 s2, 0x2070
	v_and_or_b32 v11, v11, s2, v9
	v_bfe_u32 v9, v0, 1, 3
	v_bitop3_b32 v3, v3, v9, 1 bitop3:0x6c
	v_lshlrev_b32_e32 v199, 4, v3
	v_bitop3_b32 v3, v192, v9, 2 bitop3:0x36
	v_lshlrev_b32_e32 v200, 4, v3
	v_bitop3_b32 v3, v192, v9, 4 bitop3:0x36
	v_bfe_u32 v164, v0, 2, 8
	v_lshlrev_b32_e32 v10, 3, v163
	v_lshlrev_b32_e32 v16, 4, v163
	v_bitop3_b32 v14, v42, v13, 7 bitop3:0x6c
	v_lshlrev_b32_e32 v201, 4, v3
	v_bitop3_b32 v3, v192, v9, 6 bitop3:0x36
	v_and_b32_e32 v8, 0x60, v164
	v_mov_b32_e32 v169, 0
	v_bfe_u32 v12, v163, 4, 3
	v_and_b32_e32 v6, 0x1f80, v16
	v_lshlrev_b32_e32 v14, 4, v14
	v_and_b32_e32 v195, 8, v10
	v_lshlrev_b32_e32 v202, 4, v3
	v_lshlrev_b32_e32 v196, 2, v162
	v_and_b32_e32 v3, 64, v163
	v_lshlrev_b32_e32 v168, 8, v42
	v_bfe_u32 v5, v163, 6, 1
	v_and_b32_e32 v7, 0x1c0, v0
	v_bitop3_b32 v10, v13, v12, 1 bitop3:0x36
	v_or3_b32 v17, v14, v6, v195
	v_lshl_add_u32 v197, v162, 7, 16
	v_cmp_ne_u32_e64 s[6:7], 0, v3
	v_lshl_or_b32 v3, v192, 2, v8
	v_add_u32_e32 v167, 16, v196
	s_movk_i32 s8, 0x240
	v_lshl_add_u64 v[12:13], s[28:29], 0, v[168:169]
	v_and_b32_e32 v14, 0xf0, v16
	v_mov_b32_e32 v15, v169
	v_add_f32_e32 v193, 0x3eb60549, v2
	v_lshlrev_b32_e32 v2, 6, v5
	v_lshlrev_b32_e32 v10, 4, v10
	v_lshl_add_u32 v198, v5, 13, v197
	v_lshl_add_u32 v203, v7, 2, 16
	v_cmp_eq_u32_e64 s[4:5], 0, v5
	v_mad_u32_u24 v205, v3, s8, v167
	v_and_b32_e32 v3, 3, v0
	v_mad_u32_u24 v5, v164, s8, 16
	v_lshl_add_u64 v[12:13], v[12:13], 0, v[14:15]
	s_mov_b64 s[8:9], 0x22a00000
	v_mov_b32_e32 v7, v169
	v_or_b32_e32 v166, v8, v162
	v_or3_b32 v18, v10, v6, v195
	v_lshlrev_b32_e32 v8, 4, v3
	v_lshlrev_b32_e32 v10, 2, v3
	v_lshl_add_u64 v[170:171], v[12:13], 0, s[8:9]
	v_lshl_add_u64 v[12:13], s[28:29], 0, v[6:7]
	v_and_b32_e32 v14, 0x70, v16
	v_and_b32_e32 v3, 15, v0
	s_add_u32 s10, s28, 0x3dd80024
	v_lshlrev_b32_e32 v4, 3, v192
	v_lshl_add_u64 v[12:13], v[12:13], 0, v[14:15]
	s_mov_b64 s[8:9], 0x25a00000
	v_mov_b32_e32 v9, v169
	v_lshl_or_b32 v176, v3, 4, v168
	v_and_b32_e32 v3, 7, v0
	v_lshlrev_b32_e32 v180, 1, v2
	v_mbcnt_lo_u32_b32 v2, -1, 0
	s_mov_b32 s15, 0
	s_addc_u32 s19, s29, 0
	v_cmp_eq_u32_e64 s[0:1], 0, v163
	v_bfe_u32 v194, v0, 8, 2
	v_cmp_eq_u32_e64 s[2:3], 0, v192
	v_add_u32_e32 v204, v203, v196
	v_lshlrev_b32_e32 v191, 4, v192
	v_mov_b32_e32 v165, v169
	v_lshl_add_u64 v[172:173], v[12:13], 0, s[8:9]
	v_lshl_add_u64 v[174:175], s[22:23], 0, v[8:9]
	v_mov_b32_e32 v177, v169
	v_lshl_or_b32 v178, v3, 4, v6
	v_mov_b32_e32 v179, v169
	s_movk_i32 s34, 0xbf
	s_movk_i32 s35, 0x4000
	s_movk_i32 s36, 0xa00
	v_lshlrev_b32_e32 v182, 1, v4
	s_mov_b64 s[16:17], 0x1da00400
	s_mov_b32 s37, 0x1da00000
	s_movk_i32 s68, 0x2000
	s_movk_i32 s69, 0x6000
	s_mov_b32 s70, 0x42800000
	s_mov_b32 s18, 0x3e38aa3b
	v_add_u32_e32 v206, v5, v8
	v_mov_b32_e32 v207, 0x3727c5ac
	s_mov_b32 s71, 0x800000
	v_lshlrev_b32_e32 v168, 1, v10
	s_mov_b64 s[20:21], 0xba00a00
	s_mov_b32 s72, 0xba00000
	v_mov_b32_e32 v208, 0xa00
	v_add_u32_e32 v209, 16, v11
	v_add_u32_e32 v210, 16, v17
	v_add_u32_e32 v211, 16, v18
	v_mbcnt_hi_u32_b32 v190, -1, v2
	s_mov_b32 s73, 0
	v_lshrrev_b32_e32 v176, 3, v0
	v_bfe_u32 v177, v0, 4, 3
	v_and_b32_e32 v184, 7, v0
	v_xor_b32_e32 v177, v184, v177
	v_lshlrev_b32_e32 v176, 8, v176
	v_lshl_or_b32 v176, v177, 4, v176
	v_mov_b32_e32 v177, 0
	v_readfirstlane_b32 s101, v0
	s_lshr_b32 s101, s101, 6
	s_lshl_b32 s101, s101, 10
	s_branch .LBB0_1306

; #define K_LOAD(kt) do { sk0 = *(const bf16x8*)(kg + (size_t)(kt) * 8192); sk1 = *(const bf16x8*)(kg + (size_t)(kt) * 8192 + 4096); } while (0)
; #define V_LOAD(kt) do { sv0 = *(const bf16x8*)(vg + (size_t)(kt) * 8192); sv1 = *(const bf16x8*)(vg + (size_t)(kt) * 8192 + 4096); } while (0)
; #define K_STORE(bi) do { char* s_ = kbuf + (bi) * 16384; *(bf16x8*)(s_ + klds) = sk0; *(bf16x8*)(s_ + klds + 4096) = sk1; } while (0)
; #define V_STORE(bi) do { char* s_ = vbuf + (bi) * 16384 - 16384; \
;     s16x4 a0_ = {sv0[0], sv0[1], sv0[2], sv0[3]}, a1_ = {sv0[4], sv0[5], sv0[6], sv0[7]}; \
;     s16x4 b0_ = {sv1[0], sv1[1], sv1[2], sv1[3]}, b1_ = {sv1[4], sv1[5], sv1[6], sv1[7]}; \
;     *(s16x4*)(s_ + vlds0) = a0_; *(s16x4*)(s_ + vlds1) = a1_; *(s16x4*)(s_ + vlds0 + 8192) = b0_; *(s16x4*)(s_ + vlds1 + 8192) = b1_; } while (0)
; DEVI void attn_item(const Params& p, const int l, const int bh, const int qblk, const float lam, const float osc, char* smem) {
;     ...
;   f32x16 o[4];
; #pragma unroll
;   for (int d0 = 0; d0 < 4; ++d0)
; #pragma unroll
;     for (int r = 0; r < 16; ++r) o[d0][r] = 0.f;
;   float m_reg = -1e30f, l_reg = 0.f;
;   const int xq = (l31 >> 1) & 7;
;   f32x16 pA0, pA1, pB0, pB1;
;   K_LOAD(0); V_LOAD(0);
;   {
;     const bf16x8 tk0 = *(const bf16x8*)(kg + (size_t)8192), tk1 = *(const bf16x8*)(kg + (size_t)8192 + 4096);
;     K_STORE(0); V_STORE(0);
;     sk0 = tk0; sk1 = tk1; K_STORE(1);
;   }
;   __syncthreads();
;   QK_TILE(pA0, pA1, 0);
;   __syncthreads();
.LBB0_1316:
	s_cmp_lt_u32 s52, s77
	s_cselect_b64 s[54:55], -1, 0
	s_cmp_ge_u32 s52, s77
	s_cselect_b64 s[42:43], -1, 0
	s_and_b64 vcc, exec, s[42:43]
	v_lshl_add_u64 v[184:185], s[40:41], 0, v[176:177]
	s_cbranch_vccnz .LBB0_1318
	v_add_co_u32_e32 v146, vcc, 0x22a08000, v184
	s_nop 1
	v_addc_co_u32_e32 v147, vcc, 0, v185, vcc
	s_add_u32 m0, s101, 0x810
	s_nop 0
	global_load_lds_dwordx4 v[146:147], off
	s_add_u32 m0, s101, 0x2790
	s_nop 0
	global_load_lds_dwordx4 v[146:147], off offset:128
.LBB0_1318:
	v_lshl_add_u64 v[186:187], s[40:41], 0, v[178:179]
	v_add_co_u32_e32 v154, vcc, 0x25a04000, v186
	s_nop 1
	v_addc_co_u32_e32 v155, vcc, 0, v187, vcc
	v_add_co_u32_e32 v158, vcc, 0x25a06000, v186
	s_nop 1
	v_addc_co_u32_e32 v159, vcc, 0, v187, vcc
	global_load_dwordx4 v[154:157], v[154:155], off
	s_nop 0
	global_load_dwordx4 v[158:161], v[158:159], off
	v_cmp_le_u32_e32 vcc, s52, v214
	s_and_saveexec_b64 s[8:9], vcc
	s_cbranch_execz .LBB0_1324
	ds_read_b128 v[82:85], v181 offset:18432
	ds_read_b128 v[114:117], v181 offset:22528
	s_waitcnt lgkmcnt(1)
	v_mfma_f32_32x32x16_bf16 v[82:97], v[82:85], v[130:133], 0
	v_max_f32_e32 v118, v67, v67
	v_max_f32_e32 v119, v66, v66
	v_max_f32_e32 v118, v119, v118
	v_max3_f32 v118, v118, v68, v69
	v_max3_f32 v118, v118, v70, v71
	v_max3_f32 v118, v118, v72, v73
	v_max3_f32 v118, v118, v74, v75
	v_max3_f32 v118, v118, v76, v77
	v_max3_f32 v118, v118, v78, v79
	v_max3_f32 v122, v118, v80, v81
	ds_read_b128 v[118:121], v183 offset:18432
	ds_read_b128 v[218:221], v183 offset:22528
	s_waitcnt lgkmcnt(1)
	v_mfma_f32_32x32x16_bf16 v[82:97], v[118:121], v[134:137], v[82:97]
	v_max3_f32 v118, v122, v98, v99
	v_max3_f32 v118, v118, v100, v101
	v_max3_f32 v118, v118, v102, v103
	v_max3_f32 v118, v118, v104, v105
	v_max3_f32 v118, v118, v106, v107
	v_max3_f32 v118, v118, v108, v109
	v_max3_f32 v118, v118, v110, v111
	v_max3_f32 v122, v118, v112, v113
	v_mov_b32_e32 v118, v122
	s_nop 1
	v_permlane32_swap_b32_e32 v122, v118
	ds_read_b128 v[222:225], v212 offset:22528
	ds_read_b128 v[226:229], v213 offset:22528
	v_max_f32_e32 v123, v118, v118
	ds_read_b128 v[118:121], v212 offset:18432
	s_waitcnt lgkmcnt(0)
	v_mfma_f32_32x32x16_bf16 v[82:97], v[118:121], v[138:141], v[82:97]
	v_max_f32_e32 v118, v122, v122
	v_max_f32_e32 v118, v118, v123
	v_sub_f32_e32 v120, v118, v188
	v_cmp_ge_f32_e32 vcc, s70, v120
	v_max_f32_e32 v119, v188, v188
	s_cmp_eq_u64 vcc, exec
	v_max_f32_e32 v118, v119, v118
	s_cselect_b64 vcc, -1, 0
	v_cndmask_b32_e32 v216, v118, v188, vcc
	v_sub_f32_e32 v118, v188, v216
	v_mul_f32_e32 v188, 0xbe38aa3b, v216
	v_mul_f32_e32 v189, 0x3e38aa3b, v118
	ds_read_b128 v[118:121], v213 offset:18432
	s_waitcnt lgkmcnt(0)
	v_mfma_f32_32x32x16_bf16 v[82:97], v[118:121], v[142:145], v[82:97]
	v_fma_f32 v66, v66, s18, v188
	v_fma_f32 v67, v67, s18, v188
	v_fma_f32 v68, v68, s18, v188
	v_fma_f32 v69, v69, s18, v188
	v_exp_f32_e32 v66, v66
	v_exp_f32_e32 v67, v67
	v_pk_fma_f32 v[70:71], v[70:71], s[18:19], v[188:189] op_sel_hi:[1,0,0]
	v_exp_f32_e32 v68, v68
	v_exp_f32_e32 v69, v69
	v_pk_fma_f32 v[72:73], v[72:73], s[18:19], v[188:189] op_sel_hi:[1,0,0]
	v_exp_f32_e32 v70, v70
	v_exp_f32_e32 v71, v71
	v_pk_fma_f32 v[74:75], v[74:75], s[18:19], v[188:189] op_sel_hi:[1,0,0]
	v_exp_f32_e32 v72, v72
	v_exp_f32_e32 v73, v73
	v_exp_f32_e32 v74, v74
	v_exp_f32_e32 v75, v75
	v_pk_add_f32 v[118:119], v[66:67], 0 op_sel_hi:[1,0]
	v_exp_f32_e32 v217, v189
	v_pk_add_f32 v[118:119], v[68:69], v[118:119]
	s_nop 0
	v_pk_add_f32 v[118:119], v[70:71], v[118:119]
	s_nop 0
	v_pk_add_f32 v[118:119], v[72:73], v[118:119]
	s_nop 0
	v_pk_add_f32 v[230:231], v[74:75], v[118:119]
	v_mfma_f32_32x32x16_bf16 v[114:129], v[114:117], v[130:133], 0
	v_mfma_f32_32x32x16_bf16 v[114:129], v[218:221], v[134:137], v[114:129]
	v_mfma_f32_32x32x16_bf16 v[114:129], v[222:225], v[138:141], v[114:129]
	v_mfma_f32_32x32x16_bf16 v[114:129], v[226:229], v[142:145], v[114:129]
	v_fma_f32 v76, v76, s18, v188
	v_fma_f32 v77, v77, s18, v188
	v_fma_f32 v78, v78, s18, v188
	v_fma_f32 v79, v79, s18, v188
	v_exp_f32_e32 v76, v76
	v_exp_f32_e32 v77, v77
	v_pk_fma_f32 v[80:81], v[80:81], s[18:19], v[188:189] op_sel_hi:[1,0,0]
	v_exp_f32_e32 v78, v78
	v_exp_f32_e32 v79, v79
	v_exp_f32_e32 v80, v80
	v_exp_f32_e32 v81, v81
	v_pk_fma_f32 v[98:99], v[98:99], s[18:19], v[188:189] op_sel_hi:[1,0,0]
	v_pk_fma_f32 v[100:101], v[100:101], s[18:19], v[188:189] op_sel_hi:[1,0,0]
	v_exp_f32_e32 v98, v98
	v_exp_f32_e32 v99, v99
	v_pk_add_f32 v[230:231], v[76:77], v[230:231]
	v_exp_f32_e32 v100, v100
	v_exp_f32_e32 v101, v101
	v_pk_add_f32 v[230:231], v[78:79], v[230:231]
	s_nop 0
	v_pk_add_f32 v[230:231], v[80:81], v[230:231]
	s_nop 0
	v_pk_add_f32 v[230:231], v[98:99], v[230:231]
	s_nop 0
	v_pk_add_f32 v[230:231], v[100:101], v[230:231]
	v_pk_fma_f32 v[102:103], v[102:103], s[18:19], v[188:189] op_sel_hi:[1,0,0]
	v_pk_fma_f32 v[104:105], v[104:105], s[18:19], v[188:189] op_sel_hi:[1,0,0]
	v_exp_f32_e32 v102, v102
	v_exp_f32_e32 v103, v103
	v_exp_f32_e32 v104, v104
	v_exp_f32_e32 v105, v105
	v_pk_fma_f32 v[106:107], v[106:107], s[18:19], v[188:189] op_sel_hi:[1,0,0]
	v_pk_fma_f32 v[108:109], v[108:109], s[18:19], v[188:189] op_sel_hi:[1,0,0]
	v_exp_f32_e32 v106, v106
	v_exp_f32_e32 v107, v107
	v_exp_f32_e32 v108, v108
	v_exp_f32_e32 v109, v109
	v_pk_fma_f32 v[110:111], v[110:111], s[18:19], v[188:189] op_sel_hi:[1,0,0]
	v_pk_add_f32 v[218:219], v[102:103], v[230:231]
	v_exp_f32_e32 v110, v110
	v_exp_f32_e32 v111, v111
	v_pk_add_f32 v[218:219], v[104:105], v[218:219]
	s_nop 0
	v_pk_add_f32 v[218:219], v[106:107], v[218:219]
	s_nop 0
	v_pk_add_f32 v[218:219], v[108:109], v[218:219]
	s_nop 0
	v_pk_add_f32 v[218:219], v[110:111], v[218:219]
	v_pk_fma_f32 v[112:113], v[112:113], s[18:19], v[188:189] op_sel_hi:[1,0,0]
	s_nop 0
	v_exp_f32_e32 v112, v112
	v_exp_f32_e32 v113, v113
	s_nop 0
	v_pk_add_f32 v[188:189], v[112:113], v[218:219]
	s_nop 0
	v_pk_add_f32 v[188:189], v[188:189], v[188:189] op_sel:[0,1] op_sel_hi:[1,0]
	s_nop 0
	v_mov_b32_e32 v189, v188
	s_nop 1
	v_permlane32_swap_b32_e32 v188, v189
	s_cbranch_vccnz .LBB0_1323
	s_waitcnt lgkmcnt(0)
	s_and_saveexec_b64 s[56:57], s[2:3]
	ds_write_b32 v204, v217
	s_or_b64 exec, exec, s[56:57]
	s_waitcnt lgkmcnt(0)
	v_add_u32_e32 v230, v203, v191
	ds_read_b128 v[218:221], v230 offset:96
	ds_read_b128 v[222:225], v230 offset:64
	ds_read_b128 v[226:229], v230 offset:32
	ds_read_b128 v[230:233], v230
	s_waitcnt lgkmcnt(0)
	s_waitcnt lgkmcnt(3)
	v_pk_mul_f32 v[62:63], v[62:63], v[218:219]
	s_waitcnt lgkmcnt(2)
	v_pk_mul_f32 v[58:59], v[58:59], v[222:223]
	s_waitcnt lgkmcnt(1)
	v_pk_mul_f32 v[54:55], v[54:55], v[226:227]
	v_pk_mul_f32 v[64:65], v[64:65], v[220:221]
	v_pk_mul_f32 v[60:61], v[60:61], v[224:225]
	v_pk_mul_f32 v[56:57], v[56:57], v[228:229]
	s_waitcnt lgkmcnt(0)
	v_pk_mul_f32 v[52:53], v[52:53], v[232:233]
	v_pk_mul_f32 v[50:51], v[50:51], v[230:231]
	v_pk_mul_f32 v[46:47], v[46:47], v[218:219]
	v_pk_mul_f32 v[42:43], v[42:43], v[222:223]
	v_pk_mul_f32 v[38:39], v[38:39], v[226:227]
	v_pk_mul_f32 v[48:49], v[48:49], v[220:221]
	v_pk_mul_f32 v[44:45], v[44:45], v[224:225]
	v_pk_mul_f32 v[40:41], v[40:41], v[228:229]
	v_pk_mul_f32 v[36:37], v[36:37], v[232:233]
	v_pk_mul_f32 v[34:35], v[34:35], v[230:231]
	v_pk_mul_f32 v[30:31], v[30:31], v[218:219]
	v_pk_mul_f32 v[26:27], v[26:27], v[222:223]
	v_pk_mul_f32 v[22:23], v[22:23], v[226:227]
	v_pk_mul_f32 v[32:33], v[32:33], v[220:221]
	v_pk_mul_f32 v[28:29], v[28:29], v[224:225]
	v_pk_mul_f32 v[24:25], v[24:25], v[228:229]
	v_pk_mul_f32 v[20:21], v[20:21], v[232:233]
	v_pk_mul_f32 v[18:19], v[18:19], v[230:231]
	v_pk_mul_f32 v[14:15], v[14:15], v[218:219]
	v_pk_mul_f32 v[10:11], v[10:11], v[222:223]
	v_pk_mul_f32 v[6:7], v[6:7], v[226:227]
	v_pk_mul_f32 v[16:17], v[16:17], v[220:221]
	v_pk_mul_f32 v[12:13], v[12:13], v[224:225]
	v_pk_mul_f32 v[8:9], v[8:9], v[228:229]
	v_pk_mul_f32 v[4:5], v[4:5], v[232:233]
	v_pk_mul_f32 v[2:3], v[2:3], v[230:231]

.LBB0_1324:
	s_or_b64 exec, exec, s[8:9]
	v_cndmask_b32_e64 v189, 0, 1, s[54:55]
	v_cmp_ne_u32_e64 s[8:9], 1, v189
	s_andn2_b64 vcc, exec, s[54:55]
	s_cbranch_vccnz .LBB0_1326
	s_waitcnt vmcnt(2)

.LBB0_1331:
	v_add_co_u32_e32 v146, vcc, 0x22a0c000, v184
	s_nop 1
	v_addc_co_u32_e32 v147, vcc, 0, v185, vcc
	s_add_u32 m0, s101, 0x4810
	s_nop 0
	global_load_lds_dwordx4 v[146:147], off
	s_add_u32 m0, s101, 0x6790
	s_nop 0
	global_load_lds_dwordx4 v[146:147], off offset:128
	s_and_b64 vcc, exec, s[8:9]
	s_cbranch_vccnz .LBB0_1328

; __global__ void __launch_bounds__(NTHR) fwd_kernel(Params p, int ph_begin, int ph_end) {
	.amdhsa_kernel _Z10fwd_kernel6Paramsii
		.amdhsa_group_segment_fixed_size 16
		.amdhsa_private_segment_fixed_size 0
		.amdhsa_kernarg_size 560
		.amdhsa_user_sgpr_count 2
		.amdhsa_user_sgpr_dispatch_ptr 0
		.amdhsa_user_sgpr_queue_ptr 0
		.amdhsa_user_sgpr_kernarg_segment_ptr 1
		.amdhsa_user_sgpr_dispatch_id 0
		.amdhsa_user_sgpr_kernarg_preload_length 0
		.amdhsa_user_sgpr_kernarg_preload_offset 0
		.amdhsa_user_sgpr_private_segment_size 0
		.amdhsa_uses_dynamic_stack 0
		.amdhsa_enable_private_segment 0
		.amdhsa_system_sgpr_workgroup_id_x 1
		.amdhsa_system_sgpr_workgroup_id_y 0
		.amdhsa_system_sgpr_workgroup_id_z 0
		.amdhsa_system_sgpr_workgroup_info 0
		.amdhsa_system_vgpr_workitem_id 2
		.amdhsa_next_free_vgpr 256
		.amdhsa_next_free_sgpr 102
		.amdhsa_accum_offset 256
		.amdhsa_reserve_vcc 1
		.amdhsa_float_round_mode_32 0
		.amdhsa_float_round_mode_16_64 0
		.amdhsa_float_denorm_mode_32 3
		.amdhsa_float_denorm_mode_16_64 3
		.amdhsa_dx10_clamp 1
		.amdhsa_ieee_mode 1
		.amdhsa_fp16_overflow 0
		.amdhsa_tg_split 0
		.amdhsa_exception_fp_ieee_invalid_op 0
		.amdhsa_exception_fp_denorm_src 0
		.amdhsa_exception_fp_ieee_div_zero 0
		.amdhsa_exception_fp_ieee_overflow 0
		.amdhsa_exception_fp_ieee_underflow 0
		.amdhsa_exception_fp_ieee_inexact 0
		.amdhsa_exception_int_div_zero 0
	.end_amdhsa_kernel

; __global__ void __launch_bounds__(NTHR) fwd_kernel(Params p, int ph_begin, int ph_end) {
amdhsa.kernels:
  - .agpr_count:     0
    .args:
      - .offset:         0
        .size:           296
        .value_kind:     by_value
      - .offset:         296
        .size:           4
        .value_kind:     by_value
      - .offset:         300
        .size:           4
        .value_kind:     by_value
      - .offset:         304
        .size:           4
        .value_kind:     hidden_block_count_x
      - .offset:         308
        .size:           4
        .value_kind:     hidden_block_count_y
      - .offset:         312
        .size:           4
        .value_kind:     hidden_block_count_z
      - .offset:         316
        .size:           2
        .value_kind:     hidden_group_size_x
      - .offset:         318
        .size:           2
        .value_kind:     hidden_group_size_y
      - .offset:         320
        .size:           2
        .value_kind:     hidden_group_size_z
      - .offset:         322
        .size:           2
        .value_kind:     hidden_remainder_x
      - .offset:         324
        .size:           2
        .value_kind:     hidden_remainder_y
      - .offset:         326
        .size:           2
        .value_kind:     hidden_remainder_z
      - .offset:         344
        .size:           8
        .value_kind:     hidden_global_offset_x
      - .offset:         352
        .size:           8
        .value_kind:     hidden_global_offset_y
      - .offset:         360
        .size:           8
        .value_kind:     hidden_global_offset_z
      - .offset:         368
        .size:           2
        .value_kind:     hidden_grid_dims
      - .offset:         392
        .size:           8
        .value_kind:     hidden_multigrid_sync_arg
      - .offset:         424
        .size:           4
        .value_kind:     hidden_dynamic_lds_size
    .group_segment_fixed_size: 16
    .kernarg_segment_align: 8
    .kernarg_segment_size: 560
    .language:       OpenCL C
    .language_version:
      - 2
      - 0
    .max_flat_workgroup_size: 512
    .name:           _Z10fwd_kernel6Paramsii
    .private_segment_fixed_size: 0
    .sgpr_count:     108
    .sgpr_spill_count: 53
    .symbol:         _Z10fwd_kernel6Paramsii.kd
    .uniform_work_group_size: 1
    .uses_dynamic_stack: false
    .vgpr_count:     256
    .vgpr_spill_count: 0
    .wavefront_size: 64
